# DIFF attention: the 16 p0 v_exp of each half-step moved from after the workgroup barrier to before it (overlap with the draining P.V MFMAs and barrier skew)
# baseline (speedup 1.0000x reference)
; template <bool FIRST> __device__ __forceinline__ void partialSM_ps(f32x16& p0, f32x16& p1, float& m_reg, float& alpha, f32x16& negm) {
;     ...
; #pragma unroll
;   for (int r = 0; r < 16; ++r) p0[r] = __builtin_amdgcn_exp2f(p0[r]);
; }
; __device__ __forceinline__ void finishSM(f32x16& p0, f32x16& p1, float alpha, float& l_reg, bf16x8& pa0, bf16x8& pa1, bf16x8& pa2, bf16x8& pa3) {
; #pragma unroll
;   for (int r = 0; r < 16; ++r) p1[r] = __builtin_amdgcn_exp2f(p1[r]);
;   float ps = 0;
; #pragma unroll
;   for (int r = 0; r < 16; ++r) ps += p0[r];
; #pragma unroll
;   for (int r = 0; r < 16; ++r) ps += p1[r];
;   { auto rr = __builtin_amdgcn_permlane32_swap(__float_as_uint(ps), __float_as_uint(ps), false, false);
;     ps = __uint_as_float(rr[0]) + __uint_as_float(rr[1]); }
;   l_reg = l_reg * alpha + ps;
;     ...
;   PK4(p0, 0, pa0); PK4(p0, 8, pa1); PK4(p1, 0, pa2); PK4(p1, 8, pa3);
; template <int DQK, int KW, bool DIFF, int SDEPTH, int QSP, int NBUF>
; __device__ __forceinline__ void attn_unit(const UnitP& P, char* lds) {
;     ...
;   f32x16 pA0, pA1, pB0, pB1; float mnA, mnB, alA, alB; bf16x8 pa0, pa1, pa2, pa3; const int NT = P.nt;
;   if constexpr (NBUF == 3) {
.LBB0_318:
	v_exp_f32_e32 v202, v114
	v_exp_f32_e32 v220, v115
	v_exp_f32_e32 v221, v116
	v_exp_f32_e32 v222, v117
	v_exp_f32_e32 v223, v118
	v_exp_f32_e32 v224, v119
	v_exp_f32_e32 v225, v120
	v_exp_f32_e32 v226, v121
	v_exp_f32_e32 v227, v122
	v_exp_f32_e32 v228, v123
	v_exp_f32_e32 v229, v124
	v_exp_f32_e32 v230, v125
	v_exp_f32_e32 v231, v126
	v_exp_f32_e32 v232, v127
	v_exp_f32_e32 v233, v128
	v_exp_f32_e32 v234, v129
	s_waitcnt lgkmcnt(0)
	s_barrier
	v_cmp_gt_f32_e32 vcc, 1.0, v203
	s_cbranch_vccz .LBB0_322
	s_and_saveexec_b64 s[8:9], s[38:39]
	ds_write_b32 v179, v203 offset:128
	s_or_b64 exec, exec, s[8:9]
	s_waitcnt lgkmcnt(0)
	v_add_u32_e32 v94, v178, v164
	ds_read_b128 v[82:85], v94 offset:224
	ds_read_b128 v[86:89], v94 offset:192
	ds_read_b128 v[90:93], v94 offset:160
	ds_read_b128 v[94:97], v94 offset:128
	s_waitcnt lgkmcnt(3)
	v_pk_mul_f32 v[14:15], v[14:15], v[82:83]
	s_waitcnt lgkmcnt(2)
	v_pk_mul_f32 v[10:11], v[10:11], v[86:87]
	s_waitcnt lgkmcnt(1)
	v_pk_mul_f32 v[6:7], v[6:7], v[90:91]
	v_pk_mul_f32 v[16:17], v[16:17], v[84:85]
	v_pk_mul_f32 v[12:13], v[12:13], v[88:89]
	v_pk_mul_f32 v[8:9], v[8:9], v[92:93]
	s_waitcnt lgkmcnt(0)
	v_pk_mul_f32 v[4:5], v[4:5], v[96:97]
	v_pk_mul_f32 v[2:3], v[2:3], v[94:95]
	v_pk_mul_f32 v[62:63], v[62:63], v[82:83]
	v_pk_mul_f32 v[58:59], v[58:59], v[86:87]
	v_pk_mul_f32 v[54:55], v[54:55], v[90:91]
	v_pk_mul_f32 v[64:65], v[64:65], v[84:85]
	v_pk_mul_f32 v[60:61], v[60:61], v[88:89]
	v_pk_mul_f32 v[56:57], v[56:57], v[92:93]
	v_pk_mul_f32 v[52:53], v[52:53], v[96:97]
	v_pk_mul_f32 v[50:51], v[50:51], v[94:95]
	v_pk_mul_f32 v[46:47], v[46:47], v[82:83]
	v_pk_mul_f32 v[42:43], v[42:43], v[86:87]
	v_pk_mul_f32 v[38:39], v[38:39], v[90:91]
	v_pk_mul_f32 v[48:49], v[48:49], v[84:85]
	v_pk_mul_f32 v[44:45], v[44:45], v[88:89]
	v_pk_mul_f32 v[40:41], v[40:41], v[92:93]
	v_pk_mul_f32 v[36:37], v[36:37], v[96:97]
	v_pk_mul_f32 v[34:35], v[34:35], v[94:95]
	v_pk_mul_f32 v[30:31], v[30:31], v[82:83]
	v_pk_mul_f32 v[26:27], v[26:27], v[86:87]
	v_pk_mul_f32 v[22:23], v[22:23], v[90:91]
	v_pk_mul_f32 v[32:33], v[32:33], v[84:85]
	v_pk_mul_f32 v[28:29], v[28:29], v[88:89]
	v_pk_mul_f32 v[24:25], v[24:25], v[92:93]
	v_pk_mul_f32 v[20:21], v[20:21], v[96:97]
	v_pk_mul_f32 v[18:19], v[18:19], v[94:95]
.LBB0_322:
	s_add_i32 s8, s12, 1
	s_cmp_lg_u32 s12, 2
	s_cselect_b32 s35, s8, 0
	v_add_u32_e32 v86, s11, v183
	ds_read_b128 v[82:85], v86 offset:49152
	v_add_u32_e32 v87, s11, v197
	ds_read_b128 v[204:207], v86 offset:57344
	ds_read_b128 v[208:211], v87 offset:49152
	ds_read_b128 v[212:215], v87 offset:57344
	v_add_u32_e32 v216, s11, v196
	v_exp_f32_e32 v235, v112
	v_exp_f32_e32 v113, v113
	s_waitcnt lgkmcnt(3)
	v_mfma_f32_32x32x16_bf16 v[114:129], v[82:85], v[142:145], v[66:81]
	s_waitcnt lgkmcnt(2)
	v_mfma_f32_32x32x16_bf16 v[82:97], v[204:207], v[142:145], v[66:81]
	ds_read_b128 v[204:207], v216 offset:49152
	ds_read_b128 v[216:219], v216 offset:57344
	s_waitcnt lgkmcnt(3)
	v_mfma_f32_32x32x16_bf16 v[114:129], v[208:211], v[138:141], v[114:129]
	s_waitcnt lgkmcnt(2)
	v_mfma_f32_32x32x16_bf16 v[82:97], v[212:215], v[138:141], v[82:97]
	v_add_u32_e32 v212, s11, v198
	ds_read_b128 v[208:211], v212 offset:49152
	ds_read_b128 v[212:215], v212 offset:57344
	s_waitcnt lgkmcnt(3)
	v_mfma_f32_32x32x16_bf16 v[114:129], v[204:207], v[134:137], v[114:129]
	v_exp_f32_e32 v206, v98
	v_add_f32_e32 v98, 0, v202
	v_add_f32_e32 v98, v220, v98
	v_add_f32_e32 v98, v221, v98
	v_add_f32_e32 v98, v222, v98
	v_add_f32_e32 v98, v223, v98
	v_add_f32_e32 v98, v224, v98
	v_add_f32_e32 v98, v225, v98
	v_add_f32_e32 v98, v226, v98
	v_add_f32_e32 v98, v227, v98
	v_add_f32_e32 v98, v228, v98
	s_waitcnt lgkmcnt(2)
	v_mfma_f32_32x32x16_bf16 v[82:97], v[216:219], v[134:137], v[82:97]
	v_add_f32_e32 v98, v229, v98
	v_add_f32_e32 v98, v230, v98
	v_add_f32_e32 v98, v231, v98
	v_exp_f32_e32 v207, v99
	v_add_f32_e32 v98, v232, v98
	v_add_f32_e32 v98, v233, v98
	v_add_f32_e32 v98, v234, v98
	s_waitcnt lgkmcnt(1)
	v_mfma_f32_32x32x16_bf16 v[114:129], v[208:211], v[130:133], v[114:129]
	v_exp_f32_e32 v208, v100
	v_exp_f32_e32 v209, v101
	v_exp_f32_e32 v210, v102
	v_add_f32_e32 v98, v206, v98
	v_exp_f32_e32 v211, v103
	v_add_f32_e32 v98, v207, v98
	v_add_f32_e32 v98, v208, v98
	s_waitcnt lgkmcnt(0)
	v_mfma_f32_32x32x16_bf16 v[82:97], v[212:215], v[130:133], v[82:97]
	v_exp_f32_e32 v212, v104
	v_exp_f32_e32 v213, v105
	v_add_f32_e32 v98, v209, v98
	v_exp_f32_e32 v214, v106
	v_add_f32_e32 v98, v210, v98
	v_exp_f32_e32 v215, v107
	v_add_f32_e32 v98, v211, v98
	v_exp_f32_e32 v216, v108
	v_add_f32_e32 v98, v212, v98
	v_exp_f32_e32 v217, v109
	v_add_f32_e32 v98, v213, v98
	v_exp_f32_e32 v218, v110
	v_add_f32_e32 v98, v214, v98
	v_exp_f32_e32 v219, v111
	v_add_f32_e32 v98, v215, v98
	v_add_f32_e32 v98, v216, v98
	v_add_f32_e32 v98, v217, v98
	v_add_f32_e32 v98, v218, v98
	v_add_f32_e32 v98, v219, v98
	v_add_f32_e32 v98, v235, v98
	v_add_f32_e32 v204, v113, v98
	v_mov_b32_e32 v205, v204
	v_cvt_pk_bf16_f32 v98, v202, v220
	v_cvt_pk_bf16_f32 v99, v221, v222
	v_cvt_pk_bf16_f32 v100, v223, v224
	v_cvt_pk_bf16_f32 v101, v225, v226
	v_cvt_pk_bf16_f32 v102, v227, v228
	v_cvt_pk_bf16_f32 v103, v229, v230
	v_cvt_pk_bf16_f32 v104, v231, v232
	v_cvt_pk_bf16_f32 v105, v233, v234
	v_cvt_pk_bf16_f32 v106, v206, v207
	v_cvt_pk_bf16_f32 v107, v208, v209
	v_cvt_pk_bf16_f32 v108, v210, v211
	v_cvt_pk_bf16_f32 v109, v212, v213
	v_cvt_pk_bf16_f32 v110, v214, v215
	v_cvt_pk_bf16_f32 v111, v216, v217
	v_cvt_pk_bf16_f32 v112, v218, v219
	v_cvt_pk_bf16_f32 v113, v235, v113
	s_nop 1
	v_permlane32_swap_b32_e32 v204, v205
	v_permlane32_swap_b32_e32 v98, v100
	v_permlane32_swap_b32_e32 v99, v101
	v_permlane32_swap_b32_e32 v102, v104
	v_permlane32_swap_b32_e32 v103, v105
	v_permlane32_swap_b32_e32 v106, v108
	v_permlane32_swap_b32_e32 v107, v109
	v_permlane32_swap_b32_e32 v110, v112
	v_permlane32_swap_b32_e32 v111, v113
	s_lshl_b32 s33, s35, 14
	s_add_i32 s36, s33, 0
	s_waitcnt vmcnt(0)
	v_add_u32_e32 v202, s36, v192
	s_cmp_ge_u32 s30, s31
	s_waitcnt vmcnt(3)
	ds_write_b128 v202, v[146:149]
	v_add_u32_e32 v202, s36, v193
	s_cselect_b64 s[8:9], -1, 0
	s_waitcnt vmcnt(2)
	ds_write_b128 v202, v[150:153]
	v_add_u32_e32 v202, s33, v195
	s_and_b64 vcc, exec, s[8:9]
	s_waitcnt vmcnt(1)
	ds_write_b128 v202, v[154:157] offset:49152
	s_waitcnt vmcnt(0)
	ds_write_b128 v202, v[158:161] offset:57344
	s_cbranch_vccnz .LBB0_324
	v_add_co_u32_e32 v146, vcc, 0xfffe0000, v166
	s_nop 1
	v_addc_co_u32_e32 v147, vcc, -1, v167, vcc
	v_add_co_u32_e32 v150, vcc, 0xfb7e0000, v166
	s_nop 1
	v_addc_co_u32_e32 v151, vcc, -1, v167, vcc
	v_add_co_u32_e32 v158, vcc, 0xfb800000, v166
	global_load_dwordx4 v[146:149], v[146:147], off
	s_nop 0
	global_load_dwordx4 v[154:157], v[150:151], off
	v_addc_co_u32_e32 v159, vcc, -1, v167, vcc
	global_load_dwordx4 v[150:153], v[166:167], off
	s_nop 0
	global_load_dwordx4 v[158:161], v[158:159], off

; #define SWRITE(b, i) do { *(bf16x8*)(V_lds + (b) * SHM_V + vst0) = sr_[i].vs0; *(bf16x8*)(V_lds + (b) * SHM_V + vst1) = sr_[i].vs1; \
;     *(bf16x8*)(K_lds + (b) * SHM_K + kdst0) = sr_[i].ks0; *(bf16x8*)(K_lds + (b) * SHM_K + kdst0 + 32 * KW * 2) = sr_[i].ks1; \
;     if constexpr (KW == 192) *(bf16x8*)(K_lds + (b) * SHM_K + kdst2) = sr_[i].ks2; } while (0)
; #define PSM(X0, X1, MN, AL, FIRST) do { if constexpr (DIFF) partialSM_ps<FIRST>(X0, X1, m_reg, AL, negm); else partialSM<DQK>(X0, X1, m_reg, MN, AL); } while (0)
; #define VM0() asm volatile("s_waitcnt vmcnt(0)" ::: "memory")
; #define WGBAR() asm volatile("s_waitcnt lgkmcnt(0)\n\ts_barrier" ::: "memory")
; template <int DQK, int KW, bool DIFF, int SDEPTH, int QSP, int NBUF>
; __device__ __forceinline__ void attn_unit(const UnitP& P, char* lds) {
;     ...
;   f32x16 pA0, pA1, pB0, pB1; float mnA, mnB, alA, alB; bf16x8 pa0, pa1, pa2, pa3; const int NT = P.nt;
;   if constexpr (NBUF == 3) {
;     ...
;     int rprev = 0, rcur = 1, rnext = 2;
;     SLOAD(0, 0); VM0(); SWRITE(0, 0); SLOAD(0, 1); WGBAR();
;     qkt<DQK, KW, QSP>(pA0, pA1, K_lds, kb, qr, qsp, negm); PSM(pA0, pA1, mnA, alA, true);
;     VM0(); SWRITE(1, 0); if (2 < NT) SLOAD(0, 2); WGBAR();
;     for (int j = 1; j + 1 < NT; j += 2) {
;       RSTEP(pB0, pB1, mnB, alB, pA0, pA1, alA, true, true, j + 2);
;       RSTEP(pA0, pA1, mnA, alA, pB0, pB1, alB, true, (j + 3 < NT), j + 3);
;     }
.LBB0_325:
	v_exp_f32_e32 v219, v114
	v_exp_f32_e32 v221, v115
	v_exp_f32_e32 v217, v116
	v_exp_f32_e32 v220, v117
	v_exp_f32_e32 v215, v118
	v_exp_f32_e32 v218, v119
	v_exp_f32_e32 v214, v120
	v_exp_f32_e32 v216, v121
	v_exp_f32_e32 v211, v122
	v_exp_f32_e32 v213, v123
	v_exp_f32_e32 v209, v124
	v_exp_f32_e32 v212, v125
	v_exp_f32_e32 v207, v126
	v_exp_f32_e32 v210, v127
	v_exp_f32_e32 v206, v128
	v_exp_f32_e32 v208, v129
	s_waitcnt lgkmcnt(0)
	s_barrier
	v_cmp_gt_f32_e32 vcc, 1.0, v202
	s_cbranch_vccz .LBB0_329
	s_and_saveexec_b64 s[10:11], s[38:39]
	ds_write_b32 v179, v202 offset:128
	s_or_b64 exec, exec, s[10:11]
	s_waitcnt lgkmcnt(0)
	v_add_u32_e32 v110, v178, v164
	ds_read_b128 v[98:101], v110 offset:224
	ds_read_b128 v[102:105], v110 offset:192
	ds_read_b128 v[106:109], v110 offset:160
	ds_read_b128 v[110:113], v110 offset:128
	s_waitcnt lgkmcnt(3)
	v_pk_mul_f32 v[14:15], v[14:15], v[98:99]
	s_waitcnt lgkmcnt(2)
	v_pk_mul_f32 v[10:11], v[10:11], v[102:103]
	s_waitcnt lgkmcnt(1)
	v_pk_mul_f32 v[6:7], v[6:7], v[106:107]
	v_pk_mul_f32 v[16:17], v[16:17], v[100:101]
	v_pk_mul_f32 v[12:13], v[12:13], v[104:105]
	v_pk_mul_f32 v[8:9], v[8:9], v[108:109]
	s_waitcnt lgkmcnt(0)
	v_pk_mul_f32 v[4:5], v[4:5], v[112:113]
	v_pk_mul_f32 v[2:3], v[2:3], v[110:111]
	v_pk_mul_f32 v[62:63], v[62:63], v[98:99]
	v_pk_mul_f32 v[58:59], v[58:59], v[102:103]
	v_pk_mul_f32 v[54:55], v[54:55], v[106:107]
	v_pk_mul_f32 v[64:65], v[64:65], v[100:101]
	v_pk_mul_f32 v[60:61], v[60:61], v[104:105]
	v_pk_mul_f32 v[56:57], v[56:57], v[108:109]
	v_pk_mul_f32 v[52:53], v[52:53], v[112:113]
	v_pk_mul_f32 v[50:51], v[50:51], v[110:111]
	v_pk_mul_f32 v[46:47], v[46:47], v[98:99]
	v_pk_mul_f32 v[42:43], v[42:43], v[102:103]
	v_pk_mul_f32 v[38:39], v[38:39], v[106:107]
	v_pk_mul_f32 v[48:49], v[48:49], v[100:101]
	v_pk_mul_f32 v[44:45], v[44:45], v[104:105]
	v_pk_mul_f32 v[40:41], v[40:41], v[108:109]
	v_pk_mul_f32 v[36:37], v[36:37], v[112:113]
	v_pk_mul_f32 v[34:35], v[34:35], v[110:111]
	v_pk_mul_f32 v[30:31], v[30:31], v[98:99]
	v_pk_mul_f32 v[26:27], v[26:27], v[102:103]
	v_pk_mul_f32 v[22:23], v[22:23], v[106:107]
	v_pk_mul_f32 v[32:33], v[32:33], v[100:101]
	v_pk_mul_f32 v[28:29], v[28:29], v[104:105]
	v_pk_mul_f32 v[24:25], v[24:25], v[108:109]
	v_pk_mul_f32 v[20:21], v[20:21], v[112:113]
	v_pk_mul_f32 v[18:19], v[18:19], v[110:111]
.LBB0_329:
	v_add_f32_e32 v98, v200, v201
	s_add_i32 s10, s35, 1
	v_fmac_f32_e32 v98, v199, v180
	v_add_f32_e32 v180, v204, v205
	s_cmp_lg_u32 s35, 2
	v_fmac_f32_e32 v180, v98, v203
	s_cselect_b32 s10, s10, 0
	v_lshl_add_u64 v[166:167], v[166:167], 0, s[88:89]
	s_add_i32 s30, s30, 2
	s_and_b64 vcc, exec, s[8:9]
	s_cbranch_vccnz .LBB0_333
	s_mov_b32 s9, s12
	s_mov_b32 s12, s10
	v_mov_b32_e32 v199, v202
	s_branch .LBB0_316
